# v8 plus pairwise-merged lgkmcnt waits in QK/PV MFMA streams
# baseline (speedup 1.0000x reference)
; #define MFMA(a, b, c) __builtin_amdgcn_mfma_f32_32x32x16_bf16((a), (b), (c), 0, 0, 0)
; DI int crow(int i, int h) { return (i & 3) + 8 * (i >> 2) + 4 * h; }
; #define SBAR() __builtin_amdgcn_sched_barrier(0)
; template <int DQK, int MODE, bool PIPE>
; DI void attn_core(const u16* __restrict__ Qg, const u16* __restrict__ Kg, const u16* __restrict__ Vtg, int ntiles,
;                   int kr_lo, int rs, int r_q, int c_q, int cs, const float* biasL, char* lds, f32x16 (&o)[4], float& l_out, int tid) {
;     ...
;   auto qk = [&](int t, f32x16& p0, f32x16& p1) {
;     const char* kb = lds + (t & 1) * A_BUF + r32 * KSTR + h * 16;
;     if (MODE != 0) {
; #pragma unroll
;       for (int i = 0; i < 16; ++i) { p0[i] = 0.f; p1[i] = 0.f; }
;     }
;     if (MODE == 0) {
;       constexpr int R = 4, NF = 2 * NKS;
;       const unsigned kaddr = (unsigned)(size_t)kb;
;       bf16x8 f[R];
;       SBAR();
;       f[0] = lds_rd128<0>(kaddr); f[1] = lds_rd128<32 * KSTR>(kaddr); f[2] = lds_rd128<32>(kaddr); f[3] = lds_rd128<32 * KSTR + 32>(kaddr);
;       SBAR();
;       __builtin_amdgcn_s_setprio(1);
;       QkStep<DQK, 0, NF, R>::run(kaddr, f, qf, p0, p1, negm);
;       __builtin_amdgcn_s_setprio(0);
;     } else {
; #pragma unroll
;       for (int ks = 0; ks < NKS; ++ks) {
;         const bf16x8 k0 = *(const bf16x8*)(kb + ks * 32), k1 = *(const bf16x8*)(kb + 32 * KSTR + ks * 32);
;         p0 = MFMA(k0, qf[ks], p0); p1 = MFMA(k1, qf[ks], p1);
;       }
;     }
;     if (MODE == 1 && t >= 4) {
;       const int kr = kr_lo + t - 4;
;       const float* brow = biasL + (kr - r_q + 7) * 31 + 15 - c_q;
; #pragma unroll
;       for (int i = 0; i < 16; ++i) {
;         const int kc0 = crow(i, h), kc1 = 32 + kc0;
;         p0[i] = ((unsigned)(kc0 - cs) < 16u) ? p0[i] + brow[kc0] : -1e30f;
;         p1[i] = ((unsigned)(kc1 - cs) < 16u) ? p1[i] + brow[kc1] : -1e30f;
;         if ((i & 3) == 3) __builtin_amdgcn_sched_barrier(0);
;       }
;     }
;   };
;   auto sm_pv = [&](int t, f32x16& p0, f32x16& p1) {
;     asm volatile("s_nop 7\n\ts_nop 7\n\ts_nop 7" ::: "memory");
;     if (!NEGM && __any(m != 0.f)) {
; #pragma unroll
;       for (int i = 0; i < 16; ++i) {
;         asm("v_sub_f32 %0, %1, %2" : "=v"(p0[i]) : "v"(p0[i]), "v"(m));
;         asm("v_sub_f32 %0, %1, %2" : "=v"(p1[i]) : "v"(p1[i]), "v"(m));
;       }
;     }
.LBB0_821:
	s_bitcmp1_b32 s6, 0
	s_cselect_b32 s7, 0xa800, 0
	s_add_i32 s19, s7, 0
	v_add3_u32 v244, s19, v225, v0
	ds_read_b128 v[66:69], v244 offset:0
	ds_read_b128 v[82:85], v244 offset:0x3200
	ds_read_b128 v[228:231], v244 offset:32
	ds_read_b128 v[232:235], v244 offset:0x3220
	s_setprio 1
	s_waitcnt lgkmcnt(2)
	v_mfma_f32_32x32x16_bf16 v[66:81], v[66:69], v[98:101], 0
	ds_read_b128 v[236:239], v244 offset:64
	v_mfma_f32_32x32x16_bf16 v[82:97], v[82:85], v[98:101], 0
	ds_read_b128 v[240:243], v244 offset:0x3240
	s_waitcnt lgkmcnt(2)
	v_mfma_f32_32x32x16_bf16 v[66:81], v[228:231], v[102:105], v[66:81]
	ds_read_b128 v[228:231], v244 offset:0x60
	v_mfma_f32_32x32x16_bf16 v[82:97], v[232:235], v[102:105], v[82:97]
	ds_read_b128 v[232:235], v244 offset:0x3260
	s_waitcnt lgkmcnt(2)
	v_mfma_f32_32x32x16_bf16 v[66:81], v[236:239], v[106:109], v[66:81]
	ds_read_b128 v[236:239], v244 offset:0x80
	v_mfma_f32_32x32x16_bf16 v[82:97], v[240:243], v[106:109], v[82:97]
	ds_read_b128 v[240:243], v244 offset:0x3280
	s_waitcnt lgkmcnt(2)
	v_mfma_f32_32x32x16_bf16 v[66:81], v[228:231], v[110:113], v[66:81]
	ds_read_b128 v[228:231], v244 offset:0xa0
	v_mfma_f32_32x32x16_bf16 v[82:97], v[232:235], v[110:113], v[82:97]
	ds_read_b128 v[232:235], v244 offset:0x32a0
	s_waitcnt lgkmcnt(2)
	v_mfma_f32_32x32x16_bf16 v[66:81], v[236:239], v[114:117], v[66:81]
	ds_read_b128 v[236:239], v244 offset:0xc0
	v_mfma_f32_32x32x16_bf16 v[82:97], v[240:243], v[114:117], v[82:97]
	ds_read_b128 v[240:243], v244 offset:0x32c0
	s_waitcnt lgkmcnt(2)
	v_mfma_f32_32x32x16_bf16 v[66:81], v[228:231], v[118:121], v[66:81]
	ds_read_b128 v[228:231], v244 offset:0xe0
	v_mfma_f32_32x32x16_bf16 v[82:97], v[232:235], v[118:121], v[82:97]
	ds_read_b128 v[232:235], v244 offset:0x32e0
	s_waitcnt lgkmcnt(2)
	v_mfma_f32_32x32x16_bf16 v[66:81], v[236:239], v[122:125], v[66:81]
	ds_read_b128 v[236:239], v244 offset:0x100
	v_mfma_f32_32x32x16_bf16 v[82:97], v[240:243], v[122:125], v[82:97]
	ds_read_b128 v[240:243], v244 offset:0x3300
	s_waitcnt lgkmcnt(2)
	v_mfma_f32_32x32x16_bf16 v[66:81], v[228:231], v[126:129], v[66:81]
	ds_read_b128 v[228:231], v244 offset:0x120
	v_mfma_f32_32x32x16_bf16 v[82:97], v[232:235], v[126:129], v[82:97]
	ds_read_b128 v[232:235], v244 offset:0x3320
	s_waitcnt lgkmcnt(2)
	v_mfma_f32_32x32x16_bf16 v[66:81], v[236:239], v[130:133], v[66:81]
	ds_read_b128 v[236:239], v244 offset:0x140
	v_mfma_f32_32x32x16_bf16 v[82:97], v[240:243], v[130:133], v[82:97]
	ds_read_b128 v[240:243], v244 offset:0x3340
	s_waitcnt lgkmcnt(2)
	v_mfma_f32_32x32x16_bf16 v[66:81], v[228:231], v[134:137], v[66:81]
	ds_read_b128 v[228:231], v244 offset:0x160
	v_mfma_f32_32x32x16_bf16 v[82:97], v[232:235], v[134:137], v[82:97]
	ds_read_b128 v[232:235], v244 offset:0x3360
	s_waitcnt lgkmcnt(2)
	v_mfma_f32_32x32x16_bf16 v[66:81], v[236:239], v[138:141], v[66:81]
	v_mfma_f32_32x32x16_bf16 v[82:97], v[240:243], v[138:141], v[82:97]
	s_waitcnt lgkmcnt(0)
	v_mfma_f32_32x32x16_bf16 v[66:81], v[228:231], v[142:145], v[66:81]
	v_mfma_f32_32x32x16_bf16 v[82:97], v[232:235], v[142:145], v[82:97]
	s_setprio 0
	s_nop 7
	s_nop 7
	v_cmp_neq_f32_e32 vcc, 0, v227
	s_cbranch_vccz .LBB0_823
	v_sub_f32 v66, v66, v227
	v_sub_f32 v82, v82, v227
	v_sub_f32 v67, v67, v227
	v_sub_f32 v83, v83, v227
	v_sub_f32 v68, v68, v227
	v_sub_f32 v84, v84, v227
	v_sub_f32 v69, v69, v227
	v_sub_f32 v85, v85, v227
	v_sub_f32 v70, v70, v227
	v_sub_f32 v86, v86, v227
	v_sub_f32 v71, v71, v227
	v_sub_f32 v87, v87, v227
	v_sub_f32 v72, v72, v227
	v_sub_f32 v88, v88, v227
	v_sub_f32 v73, v73, v227
	v_sub_f32 v89, v89, v227
	v_sub_f32 v74, v74, v227
	v_sub_f32 v90, v90, v227
	v_sub_f32 v75, v75, v227
	v_sub_f32 v91, v91, v227
	v_sub_f32 v76, v76, v227
	v_sub_f32 v92, v92, v227
	v_sub_f32 v77, v77, v227
	v_sub_f32 v93, v93, v227
	v_sub_f32 v78, v78, v227
	v_sub_f32 v94, v94, v227
	v_sub_f32 v79, v79, v227
	v_sub_f32 v95, v95, v227
	v_sub_f32 v80, v80, v227
	v_sub_f32 v96, v96, v227
	v_sub_f32 v81, v81, v227
	v_sub_f32 v97, v97, v227

; #define MFMA(a, b, c) __builtin_amdgcn_mfma_f32_32x32x16_bf16((a), (b), (c), 0, 0, 0)
; template <int N> DI void lgkm_wait() { asm volatile("s_waitcnt lgkmcnt(%0)" :: "i"(N) : "memory"); }
; #define SBAR() __builtin_amdgcn_sched_barrier(0)
;   static DI void run(unsigned vaddr, s16x4 (&lo)[R], s16x4 (&hi)[R], const f32x16& p0, const f32x16& p1, bf16x8& pfc, f32x16 (&o)[4]) {
;     constexpr int issued = (J + R < NF) ? (J + R) : NF;
;     if constexpr ((J & 3) == 0) {
;       if constexpr ((J >> 2) == 0) pfc = pack8<0>(p0);
;       else if constexpr ((J >> 2) == 1) pfc = pack8<8>(p0);
;       else if constexpr ((J >> 2) == 2) pfc = pack8<0>(p1);
;       else pfc = pack8<8>(p1);
;     }
;     lgkm_wait<2 * (issued - J - 1)>(); SBAR();
;     o[J & 3] = MFMA(__builtin_shufflevector(lo[J % R], hi[J % R], 0, 1, 2, 3, 4, 5, 6, 7), pfc, o[J & 3]);
;     SBAR();
;     if (J + R < NF) {
;       constexpr int off = ((J + R) & 3) * 32 * 136 + ((J + R) >> 2) * 32;
;       lo[J % R] = lds_rd64<off>(vaddr); hi[J % R] = lds_rd64<off + 16>(vaddr); SBAR();
;     }
;     if constexpr (J + 1 < NF) PvStep<J + 1, NF, R>::run(vaddr, lo, hi, p0, p1, pfc, o);
;   }
; template <int DQK, int MODE, bool PIPE>
; DI void attn_core(const u16* __restrict__ Qg, const u16* __restrict__ Kg, const u16* __restrict__ Vtg, int ntiles,
;                   int kr_lo, int rs, int r_q, int c_q, int cs, const float* biasL, char* lds, f32x16 (&o)[4], float& l_out, int tid) {
;     ...
;     for (int i = 0; i < 16; ++i) { p0[i] = __builtin_amdgcn_exp2f(p0[i]); p1[i] = __builtin_amdgcn_exp2f(p1[i]); ps += p0[i] + p1[i]; }
;     l += ps;
;     const char* vb = lds + (t & 1) * A_BUF + A_VOFF + r32 * 136 + h * 8;
;     {
;       bf16x8 pfc;
;       constexpr int R = PV_RING;
;       const unsigned vaddr = (unsigned)(size_t)vb;
;       s16x4 vlo[R], vhi[R];
;       SBAR();
;       vlo[0] = lds_rd64<0>(vaddr); vhi[0] = lds_rd64<16>(vaddr);
;       vlo[1] = lds_rd64<32 * 136>(vaddr); vhi[1] = lds_rd64<32 * 136 + 16>(vaddr);
;       if (R > 2) { vlo[2 % R] = lds_rd64<64 * 136>(vaddr); vhi[2 % R] = lds_rd64<64 * 136 + 16>(vaddr); }
;       if (R > 3) { vlo[3 % R] = lds_rd64<96 * 136>(vaddr); vhi[3 % R] = lds_rd64<96 * 136 + 16>(vaddr); }
;       SBAR();
;       __builtin_amdgcn_s_setprio(1);
;       PvStep<0, 16, R>::run(vaddr, vlo, vhi, p0, p1, pfc, o);
;       __builtin_amdgcn_s_setprio(0);
.LBB0_825:
	v_exp_f32_e32 v66, v66
	v_exp_f32_e32 v82, v82
	v_exp_f32_e32 v67, v67
	v_exp_f32_e32 v83, v83
	v_exp_f32_e32 v68, v68
	v_exp_f32_e32 v84, v84
	v_exp_f32_e32 v69, v69
	v_exp_f32_e32 v85, v85
	v_exp_f32_e32 v70, v70
	v_exp_f32_e32 v86, v86
	v_exp_f32_e32 v71, v71
	v_exp_f32_e32 v87, v87
	v_exp_f32_e32 v72, v72
	v_exp_f32_e32 v88, v88
	v_exp_f32_e32 v73, v73
	v_exp_f32_e32 v89, v89
	v_exp_f32_e32 v74, v74
	v_exp_f32_e32 v90, v90
	v_exp_f32_e32 v75, v75
	v_exp_f32_e32 v91, v91
	v_exp_f32_e32 v76, v76
	v_exp_f32_e32 v92, v92
	v_exp_f32_e32 v77, v77
	v_exp_f32_e32 v93, v93
	v_exp_f32_e32 v78, v78
	v_exp_f32_e32 v94, v94
	v_exp_f32_e32 v79, v79
	v_exp_f32_e32 v95, v95
	v_exp_f32_e32 v80, v80
	v_exp_f32_e32 v96, v96
	v_exp_f32_e32 v81, v81
	v_exp_f32_e32 v97, v97
	v_add_u32_e32 v228, s19, v226
	v_add3_u32 v248, v228, v168, s33
	ds_read_b64 v[228:229], v248 offset:0
	ds_read_b64 v[230:231], v248 offset:16
	ds_read_b64 v[232:233], v248 offset:0x1100
	ds_read_b64 v[234:235], v248 offset:0x1110
	ds_read_b64 v[236:237], v248 offset:0x2200
	ds_read_b64 v[238:239], v248 offset:0x2210
	ds_read_b64 v[240:241], v248 offset:0x3300
	ds_read_b64 v[242:243], v248 offset:0x3310
	s_setprio 1
	s_waitcnt lgkmcnt(4)
	v_cvt_pk_bf16_f32 v244, v66, v67
	v_cvt_pk_bf16_f32 v245, v68, v69
	v_cvt_pk_bf16_f32 v246, v70, v71
	v_cvt_pk_bf16_f32 v247, v72, v73
	s_nop 1
	v_mfma_f32_32x32x16_bf16 v[50:65], v[228:231], v[244:247], v[50:65]
	ds_read_b64 v[228:229], v248 offset:32
	ds_read_b64 v[230:231], v248 offset:48
	v_mfma_f32_32x32x16_bf16 v[34:49], v[232:235], v[244:247], v[34:49]
	ds_read_b64 v[232:233], v248 offset:0x1120
	ds_read_b64 v[234:235], v248 offset:0x1130
	s_waitcnt lgkmcnt(4)
	v_mfma_f32_32x32x16_bf16 v[18:33], v[236:239], v[244:247], v[18:33]
	ds_read_b64 v[236:237], v248 offset:0x2220
	ds_read_b64 v[238:239], v248 offset:0x2230
	v_mfma_f32_32x32x16_bf16 v[2:17], v[240:243], v[244:247], v[2:17]
	ds_read_b64 v[240:241], v248 offset:0x3320
	ds_read_b64 v[242:243], v248 offset:0x3330
	s_waitcnt lgkmcnt(4)
	v_cvt_pk_bf16_f32 v244, v74, v75
	v_cvt_pk_bf16_f32 v245, v76, v77
	v_cvt_pk_bf16_f32 v246, v78, v79
	v_cvt_pk_bf16_f32 v247, v80, v81
	s_nop 1
	v_mfma_f32_32x32x16_bf16 v[50:65], v[228:231], v[244:247], v[50:65]
	ds_read_b64 v[228:229], v248 offset:64
	ds_read_b64 v[230:231], v248 offset:0x50
	v_mfma_f32_32x32x16_bf16 v[34:49], v[232:235], v[244:247], v[34:49]
	ds_read_b64 v[232:233], v248 offset:0x1140
	ds_read_b64 v[234:235], v248 offset:0x1150
	s_waitcnt lgkmcnt(4)
	v_mfma_f32_32x32x16_bf16 v[18:33], v[236:239], v[244:247], v[18:33]
	ds_read_b64 v[236:237], v248 offset:0x2240
	ds_read_b64 v[238:239], v248 offset:0x2250
	v_mfma_f32_32x32x16_bf16 v[2:17], v[240:243], v[244:247], v[2:17]
	ds_read_b64 v[240:241], v248 offset:0x3340
	ds_read_b64 v[242:243], v248 offset:0x3350
	s_waitcnt lgkmcnt(4)
	v_cvt_pk_bf16_f32 v244, v82, v83
	v_cvt_pk_bf16_f32 v245, v84, v85
	v_cvt_pk_bf16_f32 v246, v86, v87
	v_cvt_pk_bf16_f32 v247, v88, v89
	s_nop 1
	v_mfma_f32_32x32x16_bf16 v[50:65], v[228:231], v[244:247], v[50:65]
	ds_read_b64 v[228:229], v248 offset:0x60
	ds_read_b64 v[230:231], v248 offset:0x70
	v_mfma_f32_32x32x16_bf16 v[34:49], v[232:235], v[244:247], v[34:49]
	ds_read_b64 v[232:233], v248 offset:0x1160
	ds_read_b64 v[234:235], v248 offset:0x1170
	s_waitcnt lgkmcnt(4)
	v_mfma_f32_32x32x16_bf16 v[18:33], v[236:239], v[244:247], v[18:33]
	ds_read_b64 v[236:237], v248 offset:0x2260
	ds_read_b64 v[238:239], v248 offset:0x2270
	v_mfma_f32_32x32x16_bf16 v[2:17], v[240:243], v[244:247], v[2:17]
	ds_read_b64 v[240:241], v248 offset:0x3360
	ds_read_b64 v[242:243], v248 offset:0x3370
	s_waitcnt lgkmcnt(4)
	v_cvt_pk_bf16_f32 v244, v90, v91
	v_cvt_pk_bf16_f32 v245, v92, v93
	v_cvt_pk_bf16_f32 v246, v94, v95
	v_cvt_pk_bf16_f32 v247, v96, v97
	s_nop 1
	v_mfma_f32_32x32x16_bf16 v[50:65], v[228:231], v[244:247], v[50:65]
	v_mfma_f32_32x32x16_bf16 v[34:49], v[232:235], v[244:247], v[34:49]
	s_waitcnt lgkmcnt(0)
	v_mfma_f32_32x32x16_bf16 v[18:33], v[236:239], v[244:247], v[18:33]
	v_mfma_f32_32x32x16_bf16 v[2:17], v[240:243], v[244:247], v[2:17]
	s_setprio 0
	s_andn2_b64 vcc, exec, s[10:11]
	s_cbranch_vccnz .LBB0_827
	s_bitcmp1_b32 s18, 0
	s_cselect_b32 s6, 0xa800, 0
	v_add3_u32 v228, s6, v167, v169
	v_add3_u32 v229, s6, v199, v217
	v_add3_u32 v230, s6, v220, v221
	s_waitcnt vmcnt(2)
	ds_write_b128 v228, v[146:149]
	s_waitcnt vmcnt(1)
	ds_write_b128 v229, v[154:157]
	s_waitcnt vmcnt(0)
	ds_write_b128 v230, v[162:165]

; template <int DQK, int MODE, bool PIPE>
; DI void attn_core(const u16* __restrict__ Qg, const u16* __restrict__ Kg, const u16* __restrict__ Vtg, int ntiles,
;                   int kr_lo, int rs, int r_q, int c_q, int cs, const float* biasL, char* lds, f32x16 (&o)[4], float& l_out, int tid) {
;     ...
;   auto qk = [&](int t, f32x16& p0, f32x16& p1) {
;     const char* kb = lds + (t & 1) * A_BUF + r32 * KSTR + h * 16;
;     if (MODE != 0) {
; #pragma unroll
;       for (int i = 0; i < 16; ++i) { p0[i] = 0.f; p1[i] = 0.f; }
;     }
;     if (MODE == 0) {
;       constexpr int R = 4, NF = 2 * NKS;
;       const unsigned kaddr = (unsigned)(size_t)kb;
;       bf16x8 f[R];
;       SBAR();
;       f[0] = lds_rd128<0>(kaddr); f[1] = lds_rd128<32 * KSTR>(kaddr); f[2] = lds_rd128<32>(kaddr); f[3] = lds_rd128<32 * KSTR + 32>(kaddr);
;       SBAR();
;       __builtin_amdgcn_s_setprio(1);
;       QkStep<DQK, 0, NF, R>::run(kaddr, f, qf, p0, p1, negm);
;       __builtin_amdgcn_s_setprio(0);
;     ...
;     float tmx;
;     {
;       float u[11];
; #pragma unroll
;       for (int i = 0; i < 5; ++i) {
;         asm("v_max3_f32 %0, %1, %2, %3" : "=v"(u[2 * i]) : "v"(p0[3 * i]), "v"(p0[3 * i + 1]), "v"(p0[3 * i + 2]));
;         asm("v_max3_f32 %0, %1, %2, %3" : "=v"(u[2 * i + 1]) : "v"(p1[3 * i]), "v"(p1[3 * i + 1]), "v"(p1[3 * i + 2]));
;       }
;       asm("v_max3_f32 %0, %1, %2, %3" : "=v"(u[10]) : "v"(p0[15]), "v"(p1[15]), "v"(u[0]));
;       float w0, w1, w2, w3;
;       asm("v_max3_f32 %0, %1, %2, %3" : "=v"(w0) : "v"(u[1]), "v"(u[2]), "v"(u[3]));
;       asm("v_max3_f32 %0, %1, %2, %3" : "=v"(w1) : "v"(u[4]), "v"(u[5]), "v"(u[6]));
;       asm("v_max3_f32 %0, %1, %2, %3" : "=v"(w2) : "v"(u[7]), "v"(u[8]), "v"(u[9]));
;       asm("v_max3_f32 %0, %1, %2, %3" : "=v"(w3) : "v"(u[10]), "v"(w0), "v"(w1));
;       asm("v_max_f32 %0, %1, %2" : "=v"(tmx) : "v"(w2), "v"(w3));
;     }
;     const bool t0 = (t == 0);
;     if (__any(tmx > THR || (t0 && tmx < -THR))) {
;       tmx = fmaxf(tmx, __shfl_xor(tmx, 32));
;       const float delta = t0 ? tmx : fmaxf(tmx, 0.f);
;       const float alpha = __builtin_amdgcn_exp2f(-fmaxf(delta, 0.f));
;       m += delta; l *= alpha;
; #pragma unroll
;       for (int d = 0; d < 4; ++d)
; #pragma unroll
;         for (int i = 0; i < 16; ++i) o[d][i] *= alpha;
; #pragma unroll
;       for (int i = 0; i < 16; ++i) { p0[i] -= delta; p1[i] -= delta; }
.LBB0_842:
	s_bitcmp1_b32 s15, 0
	s_cselect_b32 s15, 0xa800, 0
	v_add3_u32 v177, s15, v167, v0
	ds_read_b128 v[98:101], v177 offset:0
	ds_read_b128 v[216:219], v177 offset:0x1200
	ds_read_b128 v[220:223], v177 offset:32
	ds_read_b128 v[224:227], v177 offset:0x1220
	s_setprio 1
	s_waitcnt lgkmcnt(2)
	v_mfma_f32_32x32x16_bf16 v[82:97], v[98:101], v[114:117], v[18:33]
	ds_read_b128 v[228:231], v177 offset:64
	v_mfma_f32_32x32x16_bf16 v[98:113], v[216:219], v[114:117], v[18:33]
	ds_read_b128 v[216:219], v177 offset:0x1240
	s_waitcnt lgkmcnt(2)
	v_mfma_f32_32x32x16_bf16 v[82:97], v[220:223], v[118:121], v[82:97]
	ds_read_b128 v[220:223], v177 offset:0x60
	v_mfma_f32_32x32x16_bf16 v[98:113], v[224:227], v[118:121], v[98:113]
	ds_read_b128 v[224:227], v177 offset:0x1260
	s_waitcnt lgkmcnt(2)
	v_mfma_f32_32x32x16_bf16 v[82:97], v[228:231], v[122:125], v[82:97]
	v_mfma_f32_32x32x16_bf16 v[98:113], v[216:219], v[122:125], v[98:113]
	s_waitcnt lgkmcnt(0)
	v_mfma_f32_32x32x16_bf16 v[82:97], v[220:223], v[126:129], v[82:97]
	v_mfma_f32_32x32x16_bf16 v[98:113], v[224:227], v[126:129], v[98:113]
	s_setprio 0
	v_max3_f32 v177, v82, v83, v84
	s_nop 7
	s_nop 7
	v_max3_f32 v199, v98, v99, v100
	v_max3_f32 v216, v85, v86, v87
	v_max3_f32 v217, v101, v102, v103
	v_max3_f32 v218, v88, v89, v90
	v_max3_f32 v177, v97, v113, v177
	v_max3_f32 v219, v104, v105, v106
	v_max3_f32 v220, v91, v92, v93
	v_max3_f32 v221, v107, v108, v109
	v_max3_f32 v199, v199, v216, v217
	v_max3_f32 v222, v94, v95, v96
	v_max3_f32 v223, v110, v111, v112
	v_max3_f32 v216, v218, v219, v220
	v_max3_f32 v217, v221, v222, v223
	v_max3_f32 v177, v177, v199, v216
	v_max_f32 v177, v217, v177
	v_cmp_lt_f32_e32 vcc, s66, v177
	s_cbranch_vccz .LBB0_844
	v_and_b32_e32 v19, 64, v189
	v_xor_b32_e32 v18, 32, v189
	v_add_u32_e32 v19, 64, v19
	v_cmp_lt_i32_e32 vcc, v18, v19
	s_nop 1
	v_cndmask_b32_e32 v18, v189, v18, vcc
	v_lshlrev_b32_e32 v18, 2, v18
	ds_bpermute_b32 v18, v18, v177
	s_waitcnt lgkmcnt(0)
	v_max3_f32 v18, v177, v18, 0
	v_exp_f32_e64 v20, -v18
	v_add_f32_e32 v175, v175, v18
	v_pk_add_f32 v[82:83], v[82:83], v[18:19] op_sel_hi:[1,0] neg_lo:[0,1] neg_hi:[0,1]
	v_pk_add_f32 v[98:99], v[98:99], v[18:19] op_sel_hi:[1,0] neg_lo:[0,1] neg_hi:[0,1]
	v_pk_add_f32 v[84:85], v[84:85], v[18:19] op_sel_hi:[1,0] neg_lo:[0,1] neg_hi:[0,1]
	v_pk_add_f32 v[100:101], v[100:101], v[18:19] op_sel_hi:[1,0] neg_lo:[0,1] neg_hi:[0,1]
	v_pk_add_f32 v[86:87], v[86:87], v[18:19] op_sel_hi:[1,0] neg_lo:[0,1] neg_hi:[0,1]
	v_pk_add_f32 v[102:103], v[102:103], v[18:19] op_sel_hi:[1,0] neg_lo:[0,1] neg_hi:[0,1]
	v_pk_add_f32 v[88:89], v[88:89], v[18:19] op_sel_hi:[1,0] neg_lo:[0,1] neg_hi:[0,1]
	v_pk_add_f32 v[104:105], v[104:105], v[18:19] op_sel_hi:[1,0] neg_lo:[0,1] neg_hi:[0,1]
	v_pk_add_f32 v[90:91], v[90:91], v[18:19] op_sel_hi:[1,0] neg_lo:[0,1] neg_hi:[0,1]
	v_pk_add_f32 v[106:107], v[106:107], v[18:19] op_sel_hi:[1,0] neg_lo:[0,1] neg_hi:[0,1]
	v_pk_add_f32 v[92:93], v[92:93], v[18:19] op_sel_hi:[1,0] neg_lo:[0,1] neg_hi:[0,1]
	v_pk_add_f32 v[108:109], v[108:109], v[18:19] op_sel_hi:[1,0] neg_lo:[0,1] neg_hi:[0,1]
	v_pk_add_f32 v[94:95], v[94:95], v[18:19] op_sel_hi:[1,0] neg_lo:[0,1] neg_hi:[0,1]
	v_pk_add_f32 v[110:111], v[110:111], v[18:19] op_sel_hi:[1,0] neg_lo:[0,1] neg_hi:[0,1]
	v_pk_add_f32 v[96:97], v[96:97], v[18:19] op_sel_hi:[1,0] neg_lo:[0,1] neg_hi:[0,1]
	v_pk_add_f32 v[112:113], v[112:113], v[18:19] op_sel_hi:[1,0] neg_lo:[0,1] neg_hi:[0,1]
	v_xor_b32_e32 v18, 0x80000000, v175
	v_mul_f32_e32 v176, v176, v20
	v_pk_mul_f32 v[80:81], v[80:81], v[20:21] op_sel_hi:[1,0]
	v_pk_mul_f32 v[78:79], v[78:79], v[20:21] op_sel_hi:[1,0]
	v_pk_mul_f32 v[76:77], v[76:77], v[20:21] op_sel_hi:[1,0]
	v_pk_mul_f32 v[74:75], v[74:75], v[20:21] op_sel_hi:[1,0]
	v_pk_mul_f32 v[72:73], v[72:73], v[20:21] op_sel_hi:[1,0]
	v_pk_mul_f32 v[70:71], v[70:71], v[20:21] op_sel_hi:[1,0]
	v_pk_mul_f32 v[68:69], v[68:69], v[20:21] op_sel_hi:[1,0]
	v_pk_mul_f32 v[66:67], v[66:67], v[20:21] op_sel_hi:[1,0]
	v_pk_mul_f32 v[64:65], v[64:65], v[20:21] op_sel_hi:[1,0]
	v_pk_mul_f32 v[62:63], v[62:63], v[20:21] op_sel_hi:[1,0]
	v_pk_mul_f32 v[60:61], v[60:61], v[20:21] op_sel_hi:[1,0]
	v_pk_mul_f32 v[58:59], v[58:59], v[20:21] op_sel_hi:[1,0]
	v_pk_mul_f32 v[56:57], v[56:57], v[20:21] op_sel_hi:[1,0]
	v_pk_mul_f32 v[54:55], v[54:55], v[20:21] op_sel_hi:[1,0]
	v_pk_mul_f32 v[52:53], v[52:53], v[20:21] op_sel_hi:[1,0]
	v_pk_mul_f32 v[50:51], v[50:51], v[20:21] op_sel_hi:[1,0]
	v_pk_mul_f32 v[48:49], v[48:49], v[20:21] op_sel_hi:[1,0]
	v_pk_mul_f32 v[46:47], v[46:47], v[20:21] op_sel_hi:[1,0]
	v_pk_mul_f32 v[44:45], v[44:45], v[20:21] op_sel_hi:[1,0]
	v_pk_mul_f32 v[42:43], v[42:43], v[20:21] op_sel_hi:[1,0]
	v_pk_mul_f32 v[40:41], v[40:41], v[20:21] op_sel_hi:[1,0]
	v_pk_mul_f32 v[38:39], v[38:39], v[20:21] op_sel_hi:[1,0]
	v_pk_mul_f32 v[36:37], v[36:37], v[20:21] op_sel_hi:[1,0]
	v_pk_mul_f32 v[34:35], v[34:35], v[20:21] op_sel_hi:[1,0]
	v_pk_mul_f32 v[16:17], v[16:17], v[20:21] op_sel_hi:[1,0]
	v_pk_mul_f32 v[14:15], v[14:15], v[20:21] op_sel_hi:[1,0]
	v_pk_mul_f32 v[12:13], v[12:13], v[20:21] op_sel_hi:[1,0]
	v_pk_mul_f32 v[10:11], v[10:11], v[20:21] op_sel_hi:[1,0]
	v_pk_mul_f32 v[8:9], v[8:9], v[20:21] op_sel_hi:[1,0]
	v_pk_mul_f32 v[6:7], v[6:7], v[20:21] op_sel_hi:[1,0]
	v_pk_mul_f32 v[4:5], v[4:5], v[20:21] op_sel_hi:[1,0]
	v_pk_mul_f32 v[2:3], v[2:3], v[20:21] op_sel_hi:[1,0]
	v_mov_b32_e32 v19, v18
	v_mov_b32_e32 v20, v18
	v_mov_b32_e32 v21, v18
	v_mov_b32_e32 v22, v18
	v_mov_b32_e32 v23, v18
	v_mov_b32_e32 v24, v18
	v_mov_b32_e32 v25, v18
	v_mov_b32_e32 v26, v18
	v_mov_b32_e32 v27, v18
	v_mov_b32_e32 v28, v18
	v_mov_b32_e32 v29, v18
	v_mov_b32_e32 v30, v18
	v_mov_b32_e32 v31, v18
	v_mov_b32_e32 v32, v18
	v_mov_b32_e32 v33, v18
; #define MFMA(a, b, c) __builtin_amdgcn_mfma_f32_32x32x16_bf16((a), (b), (c), 0, 0, 0)
; template <int N> DI void lgkm_wait() { asm volatile("s_waitcnt lgkmcnt(%0)" :: "i"(N) : "memory"); }
; #define SBAR() __builtin_amdgcn_sched_barrier(0)
;   static DI void run(unsigned vaddr, s16x4 (&lo)[R], s16x4 (&hi)[R], const f32x16& p0, const f32x16& p1, bf16x8& pfc, f32x16 (&o)[4]) {
;     constexpr int issued = (J + R < NF) ? (J + R) : NF;
;     if constexpr ((J & 3) == 0) {
;       if constexpr ((J >> 2) == 0) pfc = pack8<0>(p0);
;       else if constexpr ((J >> 2) == 1) pfc = pack8<8>(p0);
;       else if constexpr ((J >> 2) == 2) pfc = pack8<0>(p1);
;       else pfc = pack8<8>(p1);
;     }
;     lgkm_wait<2 * (issued - J - 1)>(); SBAR();
;     o[J & 3] = MFMA(__builtin_shufflevector(lo[J % R], hi[J % R], 0, 1, 2, 3, 4, 5, 6, 7), pfc, o[J & 3]);
;     SBAR();
;     if (J + R < NF) {
;       constexpr int off = ((J + R) & 3) * 32 * 136 + ((J + R) >> 2) * 32;
;       lo[J % R] = lds_rd64<off>(vaddr); hi[J % R] = lds_rd64<off + 16>(vaddr); SBAR();
;     }
;     if constexpr (J + 1 < NF) PvStep<J + 1, NF, R>::run(vaddr, lo, hi, p0, p1, pfc, o);
;   }
; template <int DQK, int MODE, bool PIPE>
; DI void attn_core(const u16* __restrict__ Qg, const u16* __restrict__ Kg, const u16* __restrict__ Vtg, int ntiles,
;                   int kr_lo, int rs, int r_q, int c_q, int cs, const float* biasL, char* lds, f32x16 (&o)[4], float& l_out, int tid) {
;     ...
;     for (int i = 0; i < 16; ++i) { p0[i] = __builtin_amdgcn_exp2f(p0[i]); p1[i] = __builtin_amdgcn_exp2f(p1[i]); ps += p0[i] + p1[i]; }
;     l += ps;
;     const char* vb = lds + (t & 1) * A_BUF + A_VOFF + r32 * 136 + h * 8;
;     {
;       bf16x8 pfc;
;       constexpr int R = PV_RING;
;       const unsigned vaddr = (unsigned)(size_t)vb;
;       s16x4 vlo[R], vhi[R];
;       SBAR();
;       vlo[0] = lds_rd64<0>(vaddr); vhi[0] = lds_rd64<16>(vaddr);
;       vlo[1] = lds_rd64<32 * 136>(vaddr); vhi[1] = lds_rd64<32 * 136 + 16>(vaddr);
;       if (R > 2) { vlo[2 % R] = lds_rd64<64 * 136>(vaddr); vhi[2 % R] = lds_rd64<64 * 136 + 16>(vaddr); }
;       if (R > 3) { vlo[3 % R] = lds_rd64<96 * 136>(vaddr); vhi[3 % R] = lds_rd64<96 * 136 + 16>(vaddr); }
;       SBAR();
;       __builtin_amdgcn_s_setprio(1);
;       PvStep<0, 16, R>::run(vaddr, vlo, vhi, p0, p1, pfc, o);
;       __builtin_amdgcn_s_setprio(0);
.LBB0_844:
	v_exp_f32_e32 v82, v82
	v_exp_f32_e32 v98, v98
	v_exp_f32_e32 v83, v83
	v_exp_f32_e32 v99, v99
	v_exp_f32_e32 v84, v84
	v_exp_f32_e32 v100, v100
	v_exp_f32_e32 v85, v85
	v_exp_f32_e32 v101, v101
	v_exp_f32_e32 v86, v86
	v_exp_f32_e32 v102, v102
	v_exp_f32_e32 v87, v87
	v_exp_f32_e32 v103, v103
	v_exp_f32_e32 v88, v88
	v_exp_f32_e32 v104, v104
	v_exp_f32_e32 v89, v89
	v_exp_f32_e32 v105, v105
	v_exp_f32_e32 v90, v90
	v_exp_f32_e32 v106, v106
	v_exp_f32_e32 v91, v91
	v_exp_f32_e32 v107, v107
	v_exp_f32_e32 v92, v92
	v_exp_f32_e32 v108, v108
	v_exp_f32_e32 v93, v93
	v_exp_f32_e32 v109, v109
	v_exp_f32_e32 v94, v94
	v_exp_f32_e32 v110, v110
	v_exp_f32_e32 v95, v95
	v_exp_f32_e32 v111, v111
	v_exp_f32_e32 v96, v96
	v_exp_f32_e32 v112, v112
	v_exp_f32_e32 v97, v97
	v_exp_f32_e32 v113, v113
	v_add_u32_e32 v177, s15, v168
	v_add3_u32 v177, v177, v166, s33
	ds_read_b64 v[216:217], v177 offset:0
	ds_read_b64 v[218:219], v177 offset:16
	ds_read_b64 v[220:221], v177 offset:0x1100
	ds_read_b64 v[222:223], v177 offset:0x1110
	ds_read_b64 v[224:225], v177 offset:0x2200
	ds_read_b64 v[226:227], v177 offset:0x2210
	ds_read_b64 v[228:229], v177 offset:0x3300
	ds_read_b64 v[230:231], v177 offset:0x3310
	s_setprio 1
	s_waitcnt lgkmcnt(4)
	v_cvt_pk_bf16_f32 v232, v82, v83
	v_cvt_pk_bf16_f32 v233, v84, v85
	v_cvt_pk_bf16_f32 v234, v86, v87
	v_cvt_pk_bf16_f32 v235, v88, v89
	s_nop 1
	v_mfma_f32_32x32x16_bf16 v[66:81], v[216:219], v[232:235], v[66:81]
	ds_read_b64 v[216:217], v177 offset:32
	ds_read_b64 v[218:219], v177 offset:48
	v_mfma_f32_32x32x16_bf16 v[50:65], v[220:223], v[232:235], v[50:65]
	ds_read_b64 v[220:221], v177 offset:0x1120
	ds_read_b64 v[222:223], v177 offset:0x1130
	s_waitcnt lgkmcnt(4)
	v_mfma_f32_32x32x16_bf16 v[34:49], v[224:227], v[232:235], v[34:49]
	ds_read_b64 v[224:225], v177 offset:0x2220
	ds_read_b64 v[226:227], v177 offset:0x2230
	v_mfma_f32_32x32x16_bf16 v[2:17], v[228:231], v[232:235], v[2:17]
	ds_read_b64 v[228:229], v177 offset:0x3320
	ds_read_b64 v[230:231], v177 offset:0x3330
	s_waitcnt lgkmcnt(4)
	v_cvt_pk_bf16_f32 v232, v90, v91
	v_cvt_pk_bf16_f32 v233, v92, v93
	v_cvt_pk_bf16_f32 v234, v94, v95
	v_cvt_pk_bf16_f32 v235, v96, v97
	s_nop 1
	v_mfma_f32_32x32x16_bf16 v[66:81], v[216:219], v[232:235], v[66:81]
	ds_read_b64 v[216:217], v177 offset:64
	ds_read_b64 v[218:219], v177 offset:0x50
	v_mfma_f32_32x32x16_bf16 v[50:65], v[220:223], v[232:235], v[50:65]
	ds_read_b64 v[220:221], v177 offset:0x1140
	ds_read_b64 v[222:223], v177 offset:0x1150
	s_waitcnt lgkmcnt(4)
	v_mfma_f32_32x32x16_bf16 v[34:49], v[224:227], v[232:235], v[34:49]
	ds_read_b64 v[224:225], v177 offset:0x2240
	ds_read_b64 v[226:227], v177 offset:0x2250
	v_mfma_f32_32x32x16_bf16 v[2:17], v[228:231], v[232:235], v[2:17]
	ds_read_b64 v[228:229], v177 offset:0x3340
	ds_read_b64 v[230:231], v177 offset:0x3350
	s_waitcnt lgkmcnt(4)
	v_cvt_pk_bf16_f32 v232, v98, v99
	v_cvt_pk_bf16_f32 v233, v100, v101
	v_cvt_pk_bf16_f32 v234, v102, v103
	v_cvt_pk_bf16_f32 v235, v104, v105
	s_nop 1
	v_mfma_f32_32x32x16_bf16 v[66:81], v[216:219], v[232:235], v[66:81]
	ds_read_b64 v[216:217], v177 offset:0x60
	ds_read_b64 v[218:219], v177 offset:0x70
	v_mfma_f32_32x32x16_bf16 v[50:65], v[220:223], v[232:235], v[50:65]
	ds_read_b64 v[220:221], v177 offset:0x1160
	ds_read_b64 v[222:223], v177 offset:0x1170
	s_waitcnt lgkmcnt(4)
	v_mfma_f32_32x32x16_bf16 v[34:49], v[224:227], v[232:235], v[34:49]
	ds_read_b64 v[224:225], v177 offset:0x2260
	ds_read_b64 v[226:227], v177 offset:0x2270
	v_mfma_f32_32x32x16_bf16 v[2:17], v[228:231], v[232:235], v[2:17]
	ds_read_b64 v[228:229], v177 offset:0x3360
	ds_read_b64 v[230:231], v177 offset:0x3370
	s_waitcnt lgkmcnt(4)
	v_cvt_pk_bf16_f32 v232, v106, v107
	v_cvt_pk_bf16_f32 v233, v108, v109
	v_cvt_pk_bf16_f32 v234, v110, v111
	v_cvt_pk_bf16_f32 v235, v112, v113
	s_nop 1
	v_mfma_f32_32x32x16_bf16 v[66:81], v[216:219], v[232:235], v[66:81]
	v_mfma_f32_32x32x16_bf16 v[50:65], v[220:223], v[232:235], v[50:65]
	s_waitcnt lgkmcnt(0)
	v_mfma_f32_32x32x16_bf16 v[34:49], v[224:227], v[232:235], v[34:49]
	v_mfma_f32_32x32x16_bf16 v[2:17], v[228:231], v[232:235], v[2:17]
	s_setprio 0
	s_andn2_b64 vcc, exec, s[0:1]
	s_cbranch_vccnz .LBB0_846
	s_bitcmp1_b32 s14, 0
	s_cselect_b32 s0, 0xa800, 0
	v_add_u32_e32 v177, s0, v143
	s_waitcnt vmcnt(0)
	ds_write_b128 v177, v[138:141]

; template <int DQK, int MODE, bool PIPE>
; DI void attn_core(const u16* __restrict__ Qg, const u16* __restrict__ Kg, const u16* __restrict__ Vtg, int ntiles,
;                   int kr_lo, int rs, int r_q, int c_q, int cs, const float* biasL, char* lds, f32x16 (&o)[4], float& l_out, int tid) {
;     ...
;   auto qk = [&](int t, f32x16& p0, f32x16& p1) {
;     const char* kb = lds + (t & 1) * A_BUF + r32 * KSTR + h * 16;
;     if (MODE != 0) {
; #pragma unroll
;       for (int i = 0; i < 16; ++i) { p0[i] = 0.f; p1[i] = 0.f; }
;     }
;     if (MODE == 0) {
;       constexpr int R = 4, NF = 2 * NKS;
;       const unsigned kaddr = (unsigned)(size_t)kb;
;       bf16x8 f[R];
;       SBAR();
;       f[0] = lds_rd128<0>(kaddr); f[1] = lds_rd128<32 * KSTR>(kaddr); f[2] = lds_rd128<32>(kaddr); f[3] = lds_rd128<32 * KSTR + 32>(kaddr);
;       SBAR();
;       __builtin_amdgcn_s_setprio(1);
;       QkStep<DQK, 0, NF, R>::run(kaddr, f, qf, p0, p1, negm);
;       __builtin_amdgcn_s_setprio(0);
;     ...
;     float tmx;
;     {
;       float u[11];
; #pragma unroll
;       for (int i = 0; i < 5; ++i) {
;         asm("v_max3_f32 %0, %1, %2, %3" : "=v"(u[2 * i]) : "v"(p0[3 * i]), "v"(p0[3 * i + 1]), "v"(p0[3 * i + 2]));
;         asm("v_max3_f32 %0, %1, %2, %3" : "=v"(u[2 * i + 1]) : "v"(p1[3 * i]), "v"(p1[3 * i + 1]), "v"(p1[3 * i + 2]));
;       }
;       asm("v_max3_f32 %0, %1, %2, %3" : "=v"(u[10]) : "v"(p0[15]), "v"(p1[15]), "v"(u[0]));
;       float w0, w1, w2, w3;
;       asm("v_max3_f32 %0, %1, %2, %3" : "=v"(w0) : "v"(u[1]), "v"(u[2]), "v"(u[3]));
;       asm("v_max3_f32 %0, %1, %2, %3" : "=v"(w1) : "v"(u[4]), "v"(u[5]), "v"(u[6]));
;       asm("v_max3_f32 %0, %1, %2, %3" : "=v"(w2) : "v"(u[7]), "v"(u[8]), "v"(u[9]));
;       asm("v_max3_f32 %0, %1, %2, %3" : "=v"(w3) : "v"(u[10]), "v"(w0), "v"(w1));
;       asm("v_max_f32 %0, %1, %2" : "=v"(tmx) : "v"(w2), "v"(w3));
;     }
;     const bool t0 = (t == 0);
;     if (__any(tmx > THR || (t0 && tmx < -THR))) {
;       tmx = fmaxf(tmx, __shfl_xor(tmx, 32));
;       const float delta = t0 ? tmx : fmaxf(tmx, 0.f);
;       const float alpha = __builtin_amdgcn_exp2f(-fmaxf(delta, 0.f));
;       m += delta; l *= alpha;
; #pragma unroll
;       for (int d = 0; d < 4; ++d)
; #pragma unroll
;         for (int i = 0; i < 16; ++i) o[d][i] *= alpha;
; #pragma unroll
;       for (int i = 0; i < 16; ++i) { p0[i] -= delta; p1[i] -= delta; }
.LBB0_858:
	s_bitcmp1_b32 s12, 0
	s_cselect_b32 s12, 0xa800, 0
	v_add3_u32 v160, s12, v167, v0
	ds_read_b128 v[98:101], v160 offset:0
	ds_read_b128 v[156:159], v160 offset:0x1200
	ds_read_b128 v[170:173], v160 offset:32
	ds_read_b128 v[174:177], v160 offset:0x1220
	s_setprio 1
	s_waitcnt lgkmcnt(2)
	v_mfma_f32_32x32x16_bf16 v[82:97], v[98:101], v[114:117], v[34:49]
	ds_read_b128 v[216:219], v160 offset:64
	v_mfma_f32_32x32x16_bf16 v[98:113], v[156:159], v[114:117], v[34:49]
	ds_read_b128 v[156:159], v160 offset:0x1240
	s_waitcnt lgkmcnt(2)
	v_mfma_f32_32x32x16_bf16 v[82:97], v[170:173], v[118:121], v[82:97]
	ds_read_b128 v[170:173], v160 offset:0x60
	v_mfma_f32_32x32x16_bf16 v[98:113], v[174:177], v[118:121], v[98:113]
	ds_read_b128 v[174:177], v160 offset:0x1260
	s_waitcnt lgkmcnt(2)
	v_mfma_f32_32x32x16_bf16 v[82:97], v[216:219], v[122:125], v[82:97]
	v_mfma_f32_32x32x16_bf16 v[98:113], v[156:159], v[122:125], v[98:113]
	s_waitcnt lgkmcnt(0)
	v_mfma_f32_32x32x16_bf16 v[82:97], v[170:173], v[126:129], v[82:97]
	v_mfma_f32_32x32x16_bf16 v[98:113], v[174:177], v[126:129], v[98:113]
	s_setprio 0
	v_max3_f32 v156, v82, v83, v84
	s_nop 7
	s_nop 7
	v_max3_f32 v157, v98, v99, v100
	v_max3_f32 v158, v85, v86, v87
	v_max3_f32 v159, v101, v102, v103
	v_max3_f32 v160, v88, v89, v90
	v_max3_f32 v156, v97, v113, v156
	v_max3_f32 v161, v104, v105, v106
	v_max3_f32 v163, v91, v92, v93
	v_max3_f32 v169, v107, v108, v109
	v_max3_f32 v157, v157, v158, v159
	v_max3_f32 v170, v94, v95, v96
	v_max3_f32 v171, v110, v111, v112
	v_max3_f32 v158, v160, v161, v163
	v_max3_f32 v159, v169, v170, v171
	v_max3_f32 v156, v156, v157, v158
	v_max_f32 v156, v159, v156
	v_cmp_lt_f32_e32 vcc, s66, v156
	s_cbranch_vccz .LBB0_860
	ds_bpermute_b32 v34, v162, v156
	s_waitcnt lgkmcnt(0)
	v_max3_f32 v34, v156, v34, 0
	v_exp_f32_e64 v36, -v34
	v_add_f32_e32 v154, v154, v34
	v_pk_add_f32 v[82:83], v[82:83], v[34:35] op_sel_hi:[1,0] neg_lo:[0,1] neg_hi:[0,1]
	v_pk_add_f32 v[98:99], v[98:99], v[34:35] op_sel_hi:[1,0] neg_lo:[0,1] neg_hi:[0,1]
	v_pk_add_f32 v[84:85], v[84:85], v[34:35] op_sel_hi:[1,0] neg_lo:[0,1] neg_hi:[0,1]
	v_pk_add_f32 v[100:101], v[100:101], v[34:35] op_sel_hi:[1,0] neg_lo:[0,1] neg_hi:[0,1]
	v_pk_add_f32 v[86:87], v[86:87], v[34:35] op_sel_hi:[1,0] neg_lo:[0,1] neg_hi:[0,1]
	v_pk_add_f32 v[102:103], v[102:103], v[34:35] op_sel_hi:[1,0] neg_lo:[0,1] neg_hi:[0,1]
	v_pk_add_f32 v[88:89], v[88:89], v[34:35] op_sel_hi:[1,0] neg_lo:[0,1] neg_hi:[0,1]
	v_pk_add_f32 v[104:105], v[104:105], v[34:35] op_sel_hi:[1,0] neg_lo:[0,1] neg_hi:[0,1]
	v_pk_add_f32 v[90:91], v[90:91], v[34:35] op_sel_hi:[1,0] neg_lo:[0,1] neg_hi:[0,1]
	v_pk_add_f32 v[106:107], v[106:107], v[34:35] op_sel_hi:[1,0] neg_lo:[0,1] neg_hi:[0,1]
	v_pk_add_f32 v[92:93], v[92:93], v[34:35] op_sel_hi:[1,0] neg_lo:[0,1] neg_hi:[0,1]
	v_pk_add_f32 v[108:109], v[108:109], v[34:35] op_sel_hi:[1,0] neg_lo:[0,1] neg_hi:[0,1]
	v_pk_add_f32 v[94:95], v[94:95], v[34:35] op_sel_hi:[1,0] neg_lo:[0,1] neg_hi:[0,1]
	v_pk_add_f32 v[110:111], v[110:111], v[34:35] op_sel_hi:[1,0] neg_lo:[0,1] neg_hi:[0,1]
	v_pk_add_f32 v[96:97], v[96:97], v[34:35] op_sel_hi:[1,0] neg_lo:[0,1] neg_hi:[0,1]
	v_pk_add_f32 v[112:113], v[112:113], v[34:35] op_sel_hi:[1,0] neg_lo:[0,1] neg_hi:[0,1]
	v_xor_b32_e32 v34, 0x80000000, v154
	v_mul_f32_e32 v155, v155, v36
	v_pk_mul_f32 v[80:81], v[80:81], v[36:37] op_sel_hi:[1,0]
	v_pk_mul_f32 v[78:79], v[78:79], v[36:37] op_sel_hi:[1,0]
	v_pk_mul_f32 v[76:77], v[76:77], v[36:37] op_sel_hi:[1,0]
	v_pk_mul_f32 v[74:75], v[74:75], v[36:37] op_sel_hi:[1,0]
	v_pk_mul_f32 v[72:73], v[72:73], v[36:37] op_sel_hi:[1,0]
	v_pk_mul_f32 v[70:71], v[70:71], v[36:37] op_sel_hi:[1,0]
	v_pk_mul_f32 v[68:69], v[68:69], v[36:37] op_sel_hi:[1,0]
	v_pk_mul_f32 v[66:67], v[66:67], v[36:37] op_sel_hi:[1,0]
	v_pk_mul_f32 v[64:65], v[64:65], v[36:37] op_sel_hi:[1,0]
	v_pk_mul_f32 v[62:63], v[62:63], v[36:37] op_sel_hi:[1,0]
	v_pk_mul_f32 v[60:61], v[60:61], v[36:37] op_sel_hi:[1,0]
	v_pk_mul_f32 v[58:59], v[58:59], v[36:37] op_sel_hi:[1,0]
	v_pk_mul_f32 v[56:57], v[56:57], v[36:37] op_sel_hi:[1,0]
	v_pk_mul_f32 v[54:55], v[54:55], v[36:37] op_sel_hi:[1,0]
	v_pk_mul_f32 v[52:53], v[52:53], v[36:37] op_sel_hi:[1,0]
	v_pk_mul_f32 v[50:51], v[50:51], v[36:37] op_sel_hi:[1,0]
	v_pk_mul_f32 v[32:33], v[32:33], v[36:37] op_sel_hi:[1,0]
	v_pk_mul_f32 v[30:31], v[30:31], v[36:37] op_sel_hi:[1,0]
	v_pk_mul_f32 v[28:29], v[28:29], v[36:37] op_sel_hi:[1,0]
	v_pk_mul_f32 v[26:27], v[26:27], v[36:37] op_sel_hi:[1,0]
	v_pk_mul_f32 v[24:25], v[24:25], v[36:37] op_sel_hi:[1,0]
	v_pk_mul_f32 v[22:23], v[22:23], v[36:37] op_sel_hi:[1,0]
	v_pk_mul_f32 v[20:21], v[20:21], v[36:37] op_sel_hi:[1,0]
	v_pk_mul_f32 v[18:19], v[18:19], v[36:37] op_sel_hi:[1,0]
	v_pk_mul_f32 v[16:17], v[16:17], v[36:37] op_sel_hi:[1,0]
	v_pk_mul_f32 v[14:15], v[14:15], v[36:37] op_sel_hi:[1,0]
	v_pk_mul_f32 v[12:13], v[12:13], v[36:37] op_sel_hi:[1,0]
	v_pk_mul_f32 v[10:11], v[10:11], v[36:37] op_sel_hi:[1,0]
	v_pk_mul_f32 v[8:9], v[8:9], v[36:37] op_sel_hi:[1,0]
	v_pk_mul_f32 v[6:7], v[6:7], v[36:37] op_sel_hi:[1,0]
	v_pk_mul_f32 v[4:5], v[4:5], v[36:37] op_sel_hi:[1,0]
	v_pk_mul_f32 v[2:3], v[2:3], v[36:37] op_sel_hi:[1,0]
	v_mov_b32_e32 v35, v34
	v_mov_b32_e32 v36, v34
	v_mov_b32_e32 v37, v34
	v_mov_b32_e32 v38, v34
	v_mov_b32_e32 v39, v34
	v_mov_b32_e32 v40, v34
	v_mov_b32_e32 v41, v34
	v_mov_b32_e32 v42, v34
	v_mov_b32_e32 v43, v34
	v_mov_b32_e32 v44, v34
	v_mov_b32_e32 v45, v34
	v_mov_b32_e32 v46, v34
	v_mov_b32_e32 v47, v34
	v_mov_b32_e32 v48, v34
	v_mov_b32_e32 v49, v34
; #define MFMA(a, b, c) __builtin_amdgcn_mfma_f32_32x32x16_bf16((a), (b), (c), 0, 0, 0)
; template <int N> DI void lgkm_wait() { asm volatile("s_waitcnt lgkmcnt(%0)" :: "i"(N) : "memory"); }
; #define SBAR() __builtin_amdgcn_sched_barrier(0)
;   static DI void run(unsigned vaddr, s16x4 (&lo)[R], s16x4 (&hi)[R], const f32x16& p0, const f32x16& p1, bf16x8& pfc, f32x16 (&o)[4]) {
;     constexpr int issued = (J + R < NF) ? (J + R) : NF;
;     if constexpr ((J & 3) == 0) {
;       if constexpr ((J >> 2) == 0) pfc = pack8<0>(p0);
;       else if constexpr ((J >> 2) == 1) pfc = pack8<8>(p0);
;       else if constexpr ((J >> 2) == 2) pfc = pack8<0>(p1);
;       else pfc = pack8<8>(p1);
;     }
;     lgkm_wait<2 * (issued - J - 1)>(); SBAR();
;     o[J & 3] = MFMA(__builtin_shufflevector(lo[J % R], hi[J % R], 0, 1, 2, 3, 4, 5, 6, 7), pfc, o[J & 3]);
;     SBAR();
;     if (J + R < NF) {
;       constexpr int off = ((J + R) & 3) * 32 * 136 + ((J + R) >> 2) * 32;
;       lo[J % R] = lds_rd64<off>(vaddr); hi[J % R] = lds_rd64<off + 16>(vaddr); SBAR();
;     }
;     if constexpr (J + 1 < NF) PvStep<J + 1, NF, R>::run(vaddr, lo, hi, p0, p1, pfc, o);
;   }
; template <int DQK, int MODE, bool PIPE>
; DI void attn_core(const u16* __restrict__ Qg, const u16* __restrict__ Kg, const u16* __restrict__ Vtg, int ntiles,
;                   int kr_lo, int rs, int r_q, int c_q, int cs, const float* biasL, char* lds, f32x16 (&o)[4], float& l_out, int tid) {
;     ...
;     for (int i = 0; i < 16; ++i) { p0[i] = __builtin_amdgcn_exp2f(p0[i]); p1[i] = __builtin_amdgcn_exp2f(p1[i]); ps += p0[i] + p1[i]; }
;     l += ps;
;     const char* vb = lds + (t & 1) * A_BUF + A_VOFF + r32 * 136 + h * 8;
;     {
;       bf16x8 pfc;
;       constexpr int R = PV_RING;
;       const unsigned vaddr = (unsigned)(size_t)vb;
;       s16x4 vlo[R], vhi[R];
;       SBAR();
;       vlo[0] = lds_rd64<0>(vaddr); vhi[0] = lds_rd64<16>(vaddr);
;       vlo[1] = lds_rd64<32 * 136>(vaddr); vhi[1] = lds_rd64<32 * 136 + 16>(vaddr);
;       if (R > 2) { vlo[2 % R] = lds_rd64<64 * 136>(vaddr); vhi[2 % R] = lds_rd64<64 * 136 + 16>(vaddr); }
;       if (R > 3) { vlo[3 % R] = lds_rd64<96 * 136>(vaddr); vhi[3 % R] = lds_rd64<96 * 136 + 16>(vaddr); }
;       SBAR();
;       __builtin_amdgcn_s_setprio(1);
;       PvStep<0, 16, R>::run(vaddr, vlo, vhi, p0, p1, pfc, o);
;       __builtin_amdgcn_s_setprio(0);
.LBB0_860:
	v_exp_f32_e32 v82, v82
	v_exp_f32_e32 v98, v98
	v_exp_f32_e32 v83, v83
	v_exp_f32_e32 v99, v99
	v_exp_f32_e32 v84, v84
	v_exp_f32_e32 v100, v100
	v_exp_f32_e32 v85, v85
	v_exp_f32_e32 v101, v101
	v_exp_f32_e32 v86, v86
	v_exp_f32_e32 v102, v102
	v_exp_f32_e32 v87, v87
	v_exp_f32_e32 v103, v103
	v_exp_f32_e32 v88, v88
	v_exp_f32_e32 v104, v104
	v_exp_f32_e32 v89, v89
	v_exp_f32_e32 v105, v105
	v_exp_f32_e32 v90, v90
	v_exp_f32_e32 v106, v106
	v_exp_f32_e32 v91, v91
	v_exp_f32_e32 v107, v107
	v_exp_f32_e32 v92, v92
	v_exp_f32_e32 v108, v108
	v_exp_f32_e32 v93, v93
	v_exp_f32_e32 v109, v109
	v_exp_f32_e32 v94, v94
	v_exp_f32_e32 v110, v110
	v_exp_f32_e32 v95, v95
	v_exp_f32_e32 v111, v111
	v_exp_f32_e32 v96, v96
	v_exp_f32_e32 v112, v112
	v_exp_f32_e32 v97, v97
	v_exp_f32_e32 v113, v113
	v_add_u32_e32 v156, s12, v168
	v_add3_u32 v160, v156, v166, s33
	ds_read_b64 v[156:157], v160 offset:0
	ds_read_b64 v[158:159], v160 offset:16
	ds_read_b64 v[170:171], v160 offset:0x1100
	ds_read_b64 v[172:173], v160 offset:0x1110
	ds_read_b64 v[174:175], v160 offset:0x2200
	ds_read_b64 v[176:177], v160 offset:0x2210
	ds_read_b64 v[216:217], v160 offset:0x3300
	ds_read_b64 v[218:219], v160 offset:0x3310
	s_setprio 1
	s_waitcnt lgkmcnt(4)
	v_cvt_pk_bf16_f32 v220, v82, v83
	v_cvt_pk_bf16_f32 v221, v84, v85
	v_cvt_pk_bf16_f32 v222, v86, v87
	v_cvt_pk_bf16_f32 v223, v88, v89
	s_nop 1
	v_mfma_f32_32x32x16_bf16 v[66:81], v[156:159], v[220:223], v[66:81]
	ds_read_b64 v[156:157], v160 offset:32
	ds_read_b64 v[158:159], v160 offset:48
	v_mfma_f32_32x32x16_bf16 v[50:65], v[170:173], v[220:223], v[50:65]
	ds_read_b64 v[170:171], v160 offset:0x1120
	ds_read_b64 v[172:173], v160 offset:0x1130
	s_waitcnt lgkmcnt(4)
	v_mfma_f32_32x32x16_bf16 v[18:33], v[174:177], v[220:223], v[18:33]
	ds_read_b64 v[174:175], v160 offset:0x2220
	ds_read_b64 v[176:177], v160 offset:0x2230
	v_mfma_f32_32x32x16_bf16 v[2:17], v[216:219], v[220:223], v[2:17]
	ds_read_b64 v[216:217], v160 offset:0x3320
	ds_read_b64 v[218:219], v160 offset:0x3330
	s_waitcnt lgkmcnt(4)
	v_cvt_pk_bf16_f32 v220, v90, v91
	v_cvt_pk_bf16_f32 v221, v92, v93
	v_cvt_pk_bf16_f32 v222, v94, v95
	v_cvt_pk_bf16_f32 v223, v96, v97
	s_nop 1
	v_mfma_f32_32x32x16_bf16 v[66:81], v[156:159], v[220:223], v[66:81]
	ds_read_b64 v[156:157], v160 offset:64
	ds_read_b64 v[158:159], v160 offset:0x50
	v_mfma_f32_32x32x16_bf16 v[50:65], v[170:173], v[220:223], v[50:65]
	ds_read_b64 v[170:171], v160 offset:0x1140
	ds_read_b64 v[172:173], v160 offset:0x1150
	s_waitcnt lgkmcnt(4)
	v_mfma_f32_32x32x16_bf16 v[18:33], v[174:177], v[220:223], v[18:33]
	ds_read_b64 v[174:175], v160 offset:0x2240
	ds_read_b64 v[176:177], v160 offset:0x2250
	v_mfma_f32_32x32x16_bf16 v[2:17], v[216:219], v[220:223], v[2:17]
	ds_read_b64 v[216:217], v160 offset:0x3340
	ds_read_b64 v[218:219], v160 offset:0x3350
	s_waitcnt lgkmcnt(4)
	v_cvt_pk_bf16_f32 v220, v98, v99
	v_cvt_pk_bf16_f32 v221, v100, v101
	v_cvt_pk_bf16_f32 v222, v102, v103
	v_cvt_pk_bf16_f32 v223, v104, v105
	s_nop 1
	v_mfma_f32_32x32x16_bf16 v[66:81], v[156:159], v[220:223], v[66:81]
	ds_read_b64 v[156:157], v160 offset:0x60
	ds_read_b64 v[158:159], v160 offset:0x70
	v_mfma_f32_32x32x16_bf16 v[50:65], v[170:173], v[220:223], v[50:65]
	ds_read_b64 v[170:171], v160 offset:0x1160
	ds_read_b64 v[172:173], v160 offset:0x1170
	s_waitcnt lgkmcnt(4)
	v_mfma_f32_32x32x16_bf16 v[18:33], v[174:177], v[220:223], v[18:33]
	ds_read_b64 v[174:175], v160 offset:0x2260
	ds_read_b64 v[176:177], v160 offset:0x2270
	v_mfma_f32_32x32x16_bf16 v[2:17], v[216:219], v[220:223], v[2:17]
	ds_read_b64 v[216:217], v160 offset:0x3360
	ds_read_b64 v[218:219], v160 offset:0x3370
	s_waitcnt lgkmcnt(4)
	v_cvt_pk_bf16_f32 v220, v106, v107
	v_cvt_pk_bf16_f32 v221, v108, v109
	v_cvt_pk_bf16_f32 v222, v110, v111
	v_cvt_pk_bf16_f32 v223, v112, v113
	s_nop 1
	v_mfma_f32_32x32x16_bf16 v[66:81], v[156:159], v[220:223], v[66:81]
	v_mfma_f32_32x32x16_bf16 v[50:65], v[170:173], v[220:223], v[50:65]
	s_waitcnt lgkmcnt(0)
	v_mfma_f32_32x32x16_bf16 v[18:33], v[174:177], v[220:223], v[18:33]
	v_mfma_f32_32x32x16_bf16 v[2:17], v[216:219], v[220:223], v[2:17]
	s_setprio 0
	s_andn2_b64 vcc, exec, s[0:1]
	s_cbranch_vccnz .LBB0_862
	s_bitcmp1_b32 s11, 0
	s_cselect_b32 s0, 0xa800, 0
	v_add_u32_e32 v156, s0, v143
	s_waitcnt vmcnt(0)
	ds_write_b128 v156, v[138:141]
